# cmp_bias split over 8 waves with LDS reduce (was 256 serialized round trips in one block); LN loop-end wait vmcnt(0)->vmcnt(8); flat->global
# speedup vs baseline: 1.0111x; 1.0111x over previous
.LBB0_290:
	s_mov_b32 s0, s92
	s_add_i32 s1, s74, -1
	s_cmp_lg_u32 s0, s1
	s_cbranch_scc1 .LBB0_296
	s_load_dwordx2 s[12:13], s[90:91], 0x70
	s_load_dwordx2 s[8:9], s[90:91], 0x78
	s_load_dwordx2 s[14:15], s[90:91], 0x88
	s_load_dwordx2 s[10:11], s[90:91], 0x90
	s_load_dwordx2 s[6:7], s[90:91], 0xf0
	v_mbcnt_lo_u32_b32 v2, -1, 0
	v_mbcnt_hi_u32_b32 v2, -1, v2
	s_waitcnt lgkmcnt(0)
	v_cmp_gt_u32_e32 vcc, 32, v2
	v_mov_b32_e32 v4, s14
	v_mov_b32_e32 v6, s12
	v_mov_b32_e32 v5, s15
	v_mov_b32_e32 v8, s13
	v_cndmask_b32_e32 v4, v4, v6, vcc
	v_cndmask_b32_e32 v5, v5, v8, vcc
	v_mov_b32_e32 v6, s10
	v_mov_b32_e32 v8, s8
	v_mov_b32_e32 v7, s11
	v_mov_b32_e32 v9, s9
	v_cndmask_b32_e32 v6, v6, v8, vcc
	v_cndmask_b32_e32 v7, v7, v9, vcc
	v_and_b32_e32 v3, 31, v2
	v_lshlrev_b32_e32 v8, 4, v3
	v_mov_b32_e32 v9, 0
	v_lshl_add_u64 v[6:7], v[6:7], 0, v[8:9]
	s_lshl_b32 s0, s83, 12
	v_mov_b32_e32 v8, s0
	v_lshl_add_u64 v[6:7], v[6:7], 0, v[8:9]
	s_lshl_b32 s0, s83, 5
	v_mov_b32_e32 v8, s0
	v_lshl_add_u64 v[4:5], v[4:5], 0, v[8:9]
	v_mov_b32_e32 v10, 0
	v_mov_b32_e32 v11, 0
	v_mov_b32_e32 v12, 0
	v_mov_b32_e32 v13, 0
	s_mov_b64 s[4:5], 0x1000
	s_mov_b32 s0, 0
.Lcb_loop:
	global_load_dwordx4 v[14:17], v[4:5], off
	global_load_dwordx4 v[18:21], v[4:5], off offset:16
	global_load_dwordx4 v[22:25], v[4:5], off offset:32
	global_load_dwordx4 v[26:29], v[4:5], off offset:48
	global_load_dwordx4 v[30:33], v[4:5], off offset:64
	global_load_dwordx4 v[34:37], v[4:5], off offset:80
	global_load_dwordx4 v[38:41], v[4:5], off offset:96
	global_load_dwordx4 v[42:45], v[4:5], off offset:112
	v_lshl_add_u64 v[174:175], v[6:7], 0, s[4:5]
	v_lshl_add_u64 v[176:177], v[174:175], 0, s[4:5]
	v_lshl_add_u64 v[178:179], v[176:177], 0, s[4:5]
	global_load_dwordx4 v[46:49], v[6:7], off
	global_load_dwordx4 v[50:53], v[6:7], off offset:512
	global_load_dwordx4 v[54:57], v[6:7], off offset:1024
	global_load_dwordx4 v[58:61], v[6:7], off offset:1536
	global_load_dwordx4 v[62:65], v[6:7], off offset:2048
	global_load_dwordx4 v[66:69], v[6:7], off offset:2560
	global_load_dwordx4 v[70:73], v[6:7], off offset:3072
	global_load_dwordx4 v[74:77], v[6:7], off offset:3584
	global_load_dwordx4 v[78:81], v[174:175], off
	global_load_dwordx4 v[82:85], v[174:175], off offset:512
	global_load_dwordx4 v[86:89], v[174:175], off offset:1024
	global_load_dwordx4 v[90:93], v[174:175], off offset:1536
	global_load_dwordx4 v[94:97], v[174:175], off offset:2048
	global_load_dwordx4 v[98:101], v[174:175], off offset:2560
	global_load_dwordx4 v[102:105], v[174:175], off offset:3072
	global_load_dwordx4 v[106:109], v[174:175], off offset:3584
	global_load_dwordx4 v[110:113], v[176:177], off
	global_load_dwordx4 v[114:117], v[176:177], off offset:512
	global_load_dwordx4 v[118:121], v[176:177], off offset:1024
	global_load_dwordx4 v[122:125], v[176:177], off offset:1536
	global_load_dwordx4 v[126:129], v[176:177], off offset:2048
	global_load_dwordx4 v[130:133], v[176:177], off offset:2560
	global_load_dwordx4 v[134:137], v[176:177], off offset:3072
	global_load_dwordx4 v[138:141], v[176:177], off offset:3584
	global_load_dwordx4 v[142:145], v[178:179], off
	global_load_dwordx4 v[146:149], v[178:179], off offset:512
	global_load_dwordx4 v[150:153], v[178:179], off offset:1024
	global_load_dwordx4 v[154:157], v[178:179], off offset:1536
	global_load_dwordx4 v[158:161], v[178:179], off offset:2048
	global_load_dwordx4 v[162:165], v[178:179], off offset:2560
	global_load_dwordx4 v[166:169], v[178:179], off offset:3072
	global_load_dwordx4 v[170:173], v[178:179], off offset:3584
	v_lshl_add_u64 v[6:7], v[178:179], 0, s[4:5]
	v_lshl_add_u64 v[4:5], v[4:5], 0, 64
	v_lshl_add_u64 v[4:5], v[4:5], 0, 64
	s_add_i32 s0, s0, 1
	s_waitcnt vmcnt(0)
	v_fmac_f32_e32 v10, v14, v46
	v_fmac_f32_e32 v11, v14, v47
	v_fmac_f32_e32 v12, v14, v48
	v_fmac_f32_e32 v13, v14, v49
	v_fmac_f32_e32 v10, v15, v50
	v_fmac_f32_e32 v11, v15, v51
	v_fmac_f32_e32 v12, v15, v52
	v_fmac_f32_e32 v13, v15, v53
	v_fmac_f32_e32 v10, v16, v54
	v_fmac_f32_e32 v11, v16, v55
	v_fmac_f32_e32 v12, v16, v56
	v_fmac_f32_e32 v13, v16, v57
	v_fmac_f32_e32 v10, v17, v58
	v_fmac_f32_e32 v11, v17, v59
	v_fmac_f32_e32 v12, v17, v60
	v_fmac_f32_e32 v13, v17, v61
	v_fmac_f32_e32 v10, v18, v62
	v_fmac_f32_e32 v11, v18, v63
	v_fmac_f32_e32 v12, v18, v64
	v_fmac_f32_e32 v13, v18, v65
	v_fmac_f32_e32 v10, v19, v66
	v_fmac_f32_e32 v11, v19, v67
	v_fmac_f32_e32 v12, v19, v68
	v_fmac_f32_e32 v13, v19, v69
	v_fmac_f32_e32 v10, v20, v70
	v_fmac_f32_e32 v11, v20, v71
	v_fmac_f32_e32 v12, v20, v72
	v_fmac_f32_e32 v13, v20, v73
	v_fmac_f32_e32 v10, v21, v74
	v_fmac_f32_e32 v11, v21, v75
	v_fmac_f32_e32 v12, v21, v76
	v_fmac_f32_e32 v13, v21, v77
	v_fmac_f32_e32 v10, v22, v78
	v_fmac_f32_e32 v11, v22, v79
	v_fmac_f32_e32 v12, v22, v80
	v_fmac_f32_e32 v13, v22, v81
	v_fmac_f32_e32 v10, v23, v82
	v_fmac_f32_e32 v11, v23, v83
	v_fmac_f32_e32 v12, v23, v84
	v_fmac_f32_e32 v13, v23, v85
	v_fmac_f32_e32 v10, v24, v86
	v_fmac_f32_e32 v11, v24, v87
	v_fmac_f32_e32 v12, v24, v88
	v_fmac_f32_e32 v13, v24, v89
	v_fmac_f32_e32 v10, v25, v90
	v_fmac_f32_e32 v11, v25, v91
	v_fmac_f32_e32 v12, v25, v92
	v_fmac_f32_e32 v13, v25, v93
	v_fmac_f32_e32 v10, v26, v94
	v_fmac_f32_e32 v11, v26, v95
	v_fmac_f32_e32 v12, v26, v96
	v_fmac_f32_e32 v13, v26, v97
	v_fmac_f32_e32 v10, v27, v98
	v_fmac_f32_e32 v11, v27, v99
	v_fmac_f32_e32 v12, v27, v100
	v_fmac_f32_e32 v13, v27, v101
	v_fmac_f32_e32 v10, v28, v102
	v_fmac_f32_e32 v11, v28, v103
	v_fmac_f32_e32 v12, v28, v104
	v_fmac_f32_e32 v13, v28, v105
	v_fmac_f32_e32 v10, v29, v106
	v_fmac_f32_e32 v11, v29, v107
	v_fmac_f32_e32 v12, v29, v108
	v_fmac_f32_e32 v13, v29, v109
	v_fmac_f32_e32 v10, v30, v110
	v_fmac_f32_e32 v11, v30, v111
	v_fmac_f32_e32 v12, v30, v112
	v_fmac_f32_e32 v13, v30, v113
	v_fmac_f32_e32 v10, v31, v114
	v_fmac_f32_e32 v11, v31, v115
	v_fmac_f32_e32 v12, v31, v116
	v_fmac_f32_e32 v13, v31, v117
	v_fmac_f32_e32 v10, v32, v118
	v_fmac_f32_e32 v11, v32, v119
	v_fmac_f32_e32 v12, v32, v120
	v_fmac_f32_e32 v13, v32, v121
	v_fmac_f32_e32 v10, v33, v122
	v_fmac_f32_e32 v11, v33, v123
	v_fmac_f32_e32 v12, v33, v124
	v_fmac_f32_e32 v13, v33, v125
	v_fmac_f32_e32 v10, v34, v126
	v_fmac_f32_e32 v11, v34, v127
	v_fmac_f32_e32 v12, v34, v128
	v_fmac_f32_e32 v13, v34, v129
	v_fmac_f32_e32 v10, v35, v130
	v_fmac_f32_e32 v11, v35, v131
	v_fmac_f32_e32 v12, v35, v132
	v_fmac_f32_e32 v13, v35, v133
	v_fmac_f32_e32 v10, v36, v134
	v_fmac_f32_e32 v11, v36, v135
	v_fmac_f32_e32 v12, v36, v136
	v_fmac_f32_e32 v13, v36, v137
	v_fmac_f32_e32 v10, v37, v138
	v_fmac_f32_e32 v11, v37, v139
	v_fmac_f32_e32 v12, v37, v140
	v_fmac_f32_e32 v13, v37, v141
	v_fmac_f32_e32 v10, v38, v142
	v_fmac_f32_e32 v11, v38, v143
	v_fmac_f32_e32 v12, v38, v144
	v_fmac_f32_e32 v13, v38, v145
	v_fmac_f32_e32 v10, v39, v146
	v_fmac_f32_e32 v11, v39, v147
	v_fmac_f32_e32 v12, v39, v148
	v_fmac_f32_e32 v13, v39, v149
	v_fmac_f32_e32 v10, v40, v150
	v_fmac_f32_e32 v11, v40, v151
	v_fmac_f32_e32 v12, v40, v152
	v_fmac_f32_e32 v13, v40, v153
	v_fmac_f32_e32 v10, v41, v154
	v_fmac_f32_e32 v11, v41, v155
	v_fmac_f32_e32 v12, v41, v156
	v_fmac_f32_e32 v13, v41, v157
	v_fmac_f32_e32 v10, v42, v158
	v_fmac_f32_e32 v11, v42, v159
	v_fmac_f32_e32 v12, v42, v160
	v_fmac_f32_e32 v13, v42, v161
	v_fmac_f32_e32 v10, v43, v162
	v_fmac_f32_e32 v11, v43, v163
	v_fmac_f32_e32 v12, v43, v164
	v_fmac_f32_e32 v13, v43, v165
	v_fmac_f32_e32 v10, v44, v166
	v_fmac_f32_e32 v11, v44, v167
	v_fmac_f32_e32 v12, v44, v168
	v_fmac_f32_e32 v13, v44, v169
	v_fmac_f32_e32 v10, v45, v170
	v_fmac_f32_e32 v11, v45, v171
	v_fmac_f32_e32 v12, v45, v172
	v_fmac_f32_e32 v13, v45, v173
	s_cmp_lt_u32 s0, 16
	s_cbranch_scc1 .Lcb_loop
	s_lshl_b32 s0, s83, 8
	v_lshl_add_u32 v3, v2, 4, s0
	ds_write_b128 v3, v[10:13]
	s_waitcnt lgkmcnt(0)
	s_barrier
	v_add_u32_e32 v2, s83, v2
	s_movk_i32 s0, 0x100
	v_cmp_gt_u32_e32 vcc, s0, v2
	s_and_saveexec_b64 s[4:5], vcc
	s_cbranch_execz .Lcb_done
	v_lshlrev_b32_e32 v3, 2, v2
	v_add_u32_e32 v4, 0x10000, v3
	ds_read_b32 v10, v3
	ds_read_b32 v11, v3 offset:16384
	ds_read_b32 v12, v3 offset:32768
	ds_read_b32 v13, v3 offset:49152
	ds_read_b32 v14, v4
	ds_read_b32 v15, v4 offset:16384
	ds_read_b32 v16, v4 offset:32768
	ds_read_b32 v17, v4 offset:49152
	v_mov_b32_e32 v5, 0
	v_mov_b32_e32 v4, v3
	v_lshl_add_u64 v[4:5], s[6:7], 0, v[4:5]
	v_add_co_u32_e32 v4, vcc, 0x25400000, v4
	s_nop 1
	v_addc_co_u32_e32 v5, vcc, 0, v5, vcc
	s_waitcnt lgkmcnt(0)
	v_add_f32_e32 v10, v10, v11
	v_add_f32_e32 v10, v10, v12
	v_add_f32_e32 v10, v10, v13
	v_add_f32_e32 v10, v10, v14
	v_add_f32_e32 v10, v10, v15
	v_add_f32_e32 v10, v10, v16
	v_add_f32_e32 v10, v10, v17
	global_store_dword v[4:5], v10, off

.LBB0_900:
	s_or_b64 exec, exec, s[6:7]
	v_pk_mul_f32 v[126:127], v[126:127], v[0:1] op_sel_hi:[1,0]
	v_pk_mul_f32 v[122:123], v[122:123], v[0:1] op_sel_hi:[1,0]
	v_pk_mul_f32 v[118:119], v[118:119], v[0:1] op_sel_hi:[1,0]
	v_pk_mul_f32 v[114:115], v[114:115], v[0:1] op_sel_hi:[1,0]
	v_pk_mul_f32 v[110:111], v[110:111], v[0:1] op_sel_hi:[1,0]
	v_pk_mul_f32 v[106:107], v[106:107], v[0:1] op_sel_hi:[1,0]
	v_pk_mul_f32 v[86:87], v[86:87], v[0:1] op_sel_hi:[1,0]
	v_pk_mul_f32 v[66:67], v[66:67], v[0:1] op_sel_hi:[1,0]
	v_pk_mul_f32 v[128:129], v[128:129], v[0:1] op_sel_hi:[1,0]
	v_pk_fma_f32 v[126:127], v[18:19], v[126:127], v[26:27]
	v_pk_mul_f32 v[124:125], v[124:125], v[0:1] op_sel_hi:[1,0]
	v_pk_fma_f32 v[122:123], v[2:3], v[122:123], v[10:11]
	v_pk_mul_f32 v[120:121], v[120:121], v[0:1] op_sel_hi:[1,0]
	v_pk_fma_f32 v[118:119], v[6:7], v[118:119], v[14:15]
	v_pk_mul_f32 v[116:117], v[116:117], v[0:1] op_sel_hi:[1,0]
	v_pk_fma_f32 v[114:115], v[22:23], v[114:115], v[30:31]
	v_pk_mul_f32 v[112:113], v[112:113], v[0:1] op_sel_hi:[1,0]
	v_pk_fma_f32 v[110:111], v[34:35], v[110:111], v[42:43]
	v_pk_mul_f32 v[108:109], v[108:109], v[0:1] op_sel_hi:[1,0]
	v_pk_fma_f32 v[106:107], v[38:39], v[106:107], v[46:47]
	v_pk_mul_f32 v[88:89], v[88:89], v[0:1] op_sel_hi:[1,0]
	v_pk_fma_f32 v[86:87], v[50:51], v[86:87], v[58:59]
	v_pk_mul_f32 v[68:69], v[68:69], v[0:1] op_sel_hi:[1,0]
	v_pk_fma_f32 v[66:67], v[54:55], v[66:67], v[62:63]
	v_pk_fma_f32 v[128:129], v[20:21], v[128:129], v[28:29]
	v_cvt_pk_bf16_f32 v126, v126, v127
	v_pk_fma_f32 v[124:125], v[4:5], v[124:125], v[12:13]
	v_cvt_pk_bf16_f32 v127, v128, v129
	global_store_dwordx2 v[132:133], v[126:127], off
	v_cvt_pk_bf16_f32 v122, v122, v123
	v_cvt_pk_bf16_f32 v123, v124, v125
	global_store_dwordx2 v[132:133], v[122:123], off offset:512
	v_pk_fma_f32 v[120:121], v[8:9], v[120:121], v[16:17]
	v_cvt_pk_bf16_f32 v118, v118, v119
	v_pk_fma_f32 v[116:117], v[24:25], v[116:117], v[32:33]
	v_cvt_pk_bf16_f32 v119, v120, v121
	global_store_dwordx2 v[132:133], v[118:119], off offset:1024
	v_cvt_pk_bf16_f32 v114, v114, v115
	v_cvt_pk_bf16_f32 v115, v116, v117
	global_store_dwordx2 v[132:133], v[114:115], off offset:1536
	v_pk_fma_f32 v[112:113], v[36:37], v[112:113], v[44:45]
	v_cvt_pk_bf16_f32 v110, v110, v111
	v_pk_fma_f32 v[108:109], v[40:41], v[108:109], v[48:49]
	v_cvt_pk_bf16_f32 v111, v112, v113
	global_store_dwordx2 v[132:133], v[110:111], off offset:2048
	v_cvt_pk_bf16_f32 v106, v106, v107
	v_cvt_pk_bf16_f32 v107, v108, v109
	global_store_dwordx2 v[132:133], v[106:107], off offset:2560
	v_pk_fma_f32 v[88:89], v[52:53], v[88:89], v[60:61]
	v_cvt_pk_bf16_f32 v86, v86, v87
	v_pk_fma_f32 v[68:69], v[56:57], v[68:69], v[64:65]
	v_cvt_pk_bf16_f32 v87, v88, v89
	global_store_dwordx2 v[132:133], v[86:87], off offset:3072
	v_cvt_pk_bf16_f32 v66, v66, v67
	v_cvt_pk_bf16_f32 v67, v68, v69
	global_store_dwordx2 v[132:133], v[66:67], off offset:3584
	s_add_u32 s8, s8, s80
	s_waitcnt vmcnt(8)
	v_mov_b64_e32 v[66:67], v[90:91]
	v_mov_b64_e32 v[86:87], v[94:95]
	v_mov_b64_e32 v[108:109], v[100:101]
	v_mov_b64_e32 v[112:113], v[104:105]
	v_mov_b64_e32 v[116:117], v[72:73]
	v_mov_b64_e32 v[120:121], v[76:77]
	v_mov_b64_e32 v[124:125], v[80:81]
	v_mov_b64_e32 v[128:129], v[84:85]
	s_addc_u32 s9, s9, s81
	v_lshl_add_u64 v[132:133], v[132:133], 0, s[84:85]
	s_and_b64 vcc, exec, s[10:11]
	v_mov_b64_e32 v[68:69], v[92:93]
	v_mov_b64_e32 v[88:89], v[96:97]
	v_mov_b64_e32 v[106:107], v[98:99]
	v_mov_b64_e32 v[110:111], v[102:103]
	v_mov_b64_e32 v[114:115], v[70:71]
	v_mov_b64_e32 v[118:119], v[74:75]
	v_mov_b64_e32 v[122:123], v[78:79]
	v_mov_b64_e32 v[126:127], v[82:83]
	s_cbranch_vccnz .LBB0_905

.LBB0_1319:
	s_or_b64 exec, exec, s[6:7]
	v_pk_mul_f32 v[126:127], v[126:127], v[0:1] op_sel_hi:[1,0]
	v_pk_mul_f32 v[122:123], v[122:123], v[0:1] op_sel_hi:[1,0]
	v_pk_mul_f32 v[118:119], v[118:119], v[0:1] op_sel_hi:[1,0]
	v_pk_mul_f32 v[114:115], v[114:115], v[0:1] op_sel_hi:[1,0]
	v_pk_mul_f32 v[110:111], v[110:111], v[0:1] op_sel_hi:[1,0]
	v_pk_mul_f32 v[106:107], v[106:107], v[0:1] op_sel_hi:[1,0]
	v_pk_mul_f32 v[86:87], v[86:87], v[0:1] op_sel_hi:[1,0]
	v_pk_mul_f32 v[66:67], v[66:67], v[0:1] op_sel_hi:[1,0]
	v_pk_mul_f32 v[128:129], v[128:129], v[0:1] op_sel_hi:[1,0]
	v_pk_fma_f32 v[126:127], v[2:3], v[126:127], v[10:11]
	v_pk_mul_f32 v[124:125], v[124:125], v[0:1] op_sel_hi:[1,0]
	v_pk_fma_f32 v[122:123], v[6:7], v[122:123], v[14:15]
	v_pk_mul_f32 v[120:121], v[120:121], v[0:1] op_sel_hi:[1,0]
	v_pk_fma_f32 v[118:119], v[18:19], v[118:119], v[26:27]
	v_pk_mul_f32 v[116:117], v[116:117], v[0:1] op_sel_hi:[1,0]
	v_pk_fma_f32 v[114:115], v[22:23], v[114:115], v[30:31]
	v_pk_mul_f32 v[112:113], v[112:113], v[0:1] op_sel_hi:[1,0]
	v_pk_fma_f32 v[110:111], v[34:35], v[110:111], v[42:43]
	v_pk_mul_f32 v[108:109], v[108:109], v[0:1] op_sel_hi:[1,0]
	v_pk_fma_f32 v[106:107], v[38:39], v[106:107], v[46:47]
	v_pk_mul_f32 v[88:89], v[88:89], v[0:1] op_sel_hi:[1,0]
	v_pk_fma_f32 v[86:87], v[50:51], v[86:87], v[58:59]
	v_pk_mul_f32 v[68:69], v[68:69], v[0:1] op_sel_hi:[1,0]
	v_pk_fma_f32 v[66:67], v[54:55], v[66:67], v[62:63]
	v_pk_fma_f32 v[128:129], v[4:5], v[128:129], v[12:13]
	v_cvt_pk_bf16_f32 v126, v126, v127
	v_pk_fma_f32 v[124:125], v[8:9], v[124:125], v[16:17]
	v_cvt_pk_bf16_f32 v127, v128, v129
	global_store_dwordx2 v[132:133], v[126:127], off
	v_cvt_pk_bf16_f32 v122, v122, v123
	v_cvt_pk_bf16_f32 v123, v124, v125
	global_store_dwordx2 v[132:133], v[122:123], off offset:512
	v_pk_fma_f32 v[120:121], v[20:21], v[120:121], v[28:29]
	v_cvt_pk_bf16_f32 v118, v118, v119
	v_pk_fma_f32 v[116:117], v[24:25], v[116:117], v[32:33]
	v_cvt_pk_bf16_f32 v119, v120, v121
	global_store_dwordx2 v[132:133], v[118:119], off offset:1024
	v_cvt_pk_bf16_f32 v114, v114, v115
	v_cvt_pk_bf16_f32 v115, v116, v117
	global_store_dwordx2 v[132:133], v[114:115], off offset:1536
	v_pk_fma_f32 v[112:113], v[36:37], v[112:113], v[44:45]
	v_cvt_pk_bf16_f32 v110, v110, v111
	v_pk_fma_f32 v[108:109], v[40:41], v[108:109], v[48:49]
	v_cvt_pk_bf16_f32 v111, v112, v113
	global_store_dwordx2 v[132:133], v[110:111], off offset:2048
	v_cvt_pk_bf16_f32 v106, v106, v107
	v_cvt_pk_bf16_f32 v107, v108, v109
	global_store_dwordx2 v[132:133], v[106:107], off offset:2560
	v_pk_fma_f32 v[88:89], v[52:53], v[88:89], v[60:61]
	v_cvt_pk_bf16_f32 v86, v86, v87
	v_pk_fma_f32 v[68:69], v[56:57], v[68:69], v[64:65]
	v_cvt_pk_bf16_f32 v87, v88, v89
	global_store_dwordx2 v[132:133], v[86:87], off offset:3072
	v_cvt_pk_bf16_f32 v66, v66, v67
	v_cvt_pk_bf16_f32 v67, v68, v69
	global_store_dwordx2 v[132:133], v[66:67], off offset:3584
	s_add_u32 s8, s8, s80
	s_waitcnt vmcnt(8)
	v_mov_b64_e32 v[66:67], v[90:91]
	v_mov_b64_e32 v[86:87], v[94:95]
	v_mov_b64_e32 v[108:109], v[100:101]
	v_mov_b64_e32 v[112:113], v[104:105]
	v_mov_b64_e32 v[116:117], v[72:73]
	v_mov_b64_e32 v[120:121], v[76:77]
	v_mov_b64_e32 v[124:125], v[80:81]
	v_mov_b64_e32 v[128:129], v[84:85]
	s_addc_u32 s9, s9, s81
	v_lshl_add_u64 v[132:133], v[132:133], 0, s[84:85]
	s_and_b64 vcc, exec, s[10:11]
	v_mov_b64_e32 v[68:69], v[92:93]
	v_mov_b64_e32 v[88:89], v[96:97]
	v_mov_b64_e32 v[106:107], v[98:99]
	v_mov_b64_e32 v[110:111], v[102:103]
	v_mov_b64_e32 v[114:115], v[70:71]
	v_mov_b64_e32 v[118:119], v[74:75]
	v_mov_b64_e32 v[122:123], v[78:79]
	v_mov_b64_e32 v[126:127], v[82:83]
	s_cbranch_vccnz .LBB0_1324

.LBB0_1519:
	s_or_b64 exec, exec, s[6:7]
	v_pk_mul_f32 v[126:127], v[126:127], v[0:1] op_sel_hi:[1,0]
	v_pk_mul_f32 v[122:123], v[122:123], v[0:1] op_sel_hi:[1,0]
	v_pk_mul_f32 v[118:119], v[118:119], v[0:1] op_sel_hi:[1,0]
	v_pk_mul_f32 v[114:115], v[114:115], v[0:1] op_sel_hi:[1,0]
	v_pk_mul_f32 v[110:111], v[110:111], v[0:1] op_sel_hi:[1,0]
	v_pk_mul_f32 v[106:107], v[106:107], v[0:1] op_sel_hi:[1,0]
	v_pk_mul_f32 v[86:87], v[86:87], v[0:1] op_sel_hi:[1,0]
	v_pk_mul_f32 v[66:67], v[66:67], v[0:1] op_sel_hi:[1,0]
	v_pk_mul_f32 v[128:129], v[128:129], v[0:1] op_sel_hi:[1,0]
	v_pk_fma_f32 v[126:127], v[2:3], v[126:127], v[10:11]
	v_pk_mul_f32 v[124:125], v[124:125], v[0:1] op_sel_hi:[1,0]
	v_pk_fma_f32 v[122:123], v[6:7], v[122:123], v[14:15]
	v_pk_mul_f32 v[120:121], v[120:121], v[0:1] op_sel_hi:[1,0]
	v_pk_fma_f32 v[118:119], v[18:19], v[118:119], v[26:27]
	v_pk_mul_f32 v[116:117], v[116:117], v[0:1] op_sel_hi:[1,0]
	v_pk_fma_f32 v[114:115], v[22:23], v[114:115], v[30:31]
	v_pk_mul_f32 v[112:113], v[112:113], v[0:1] op_sel_hi:[1,0]
	v_pk_fma_f32 v[110:111], v[34:35], v[110:111], v[42:43]
	v_pk_mul_f32 v[108:109], v[108:109], v[0:1] op_sel_hi:[1,0]
	v_pk_fma_f32 v[106:107], v[38:39], v[106:107], v[46:47]
	v_pk_mul_f32 v[88:89], v[88:89], v[0:1] op_sel_hi:[1,0]
	v_pk_fma_f32 v[86:87], v[50:51], v[86:87], v[58:59]
	v_pk_mul_f32 v[68:69], v[68:69], v[0:1] op_sel_hi:[1,0]
	v_pk_fma_f32 v[66:67], v[54:55], v[66:67], v[62:63]
	v_pk_fma_f32 v[128:129], v[4:5], v[128:129], v[12:13]
	v_cvt_pk_bf16_f32 v126, v126, v127
	v_pk_fma_f32 v[124:125], v[8:9], v[124:125], v[16:17]
	v_cvt_pk_bf16_f32 v127, v128, v129
	global_store_dwordx2 v[132:133], v[126:127], off
	v_cvt_pk_bf16_f32 v122, v122, v123
	v_cvt_pk_bf16_f32 v123, v124, v125
	global_store_dwordx2 v[132:133], v[122:123], off offset:512
	v_pk_fma_f32 v[120:121], v[20:21], v[120:121], v[28:29]
	v_cvt_pk_bf16_f32 v118, v118, v119
	v_pk_fma_f32 v[116:117], v[24:25], v[116:117], v[32:33]
	v_cvt_pk_bf16_f32 v119, v120, v121
	global_store_dwordx2 v[132:133], v[118:119], off offset:1024
	v_cvt_pk_bf16_f32 v114, v114, v115
	v_cvt_pk_bf16_f32 v115, v116, v117
	global_store_dwordx2 v[132:133], v[114:115], off offset:1536
	v_pk_fma_f32 v[112:113], v[36:37], v[112:113], v[44:45]
	v_cvt_pk_bf16_f32 v110, v110, v111
	v_pk_fma_f32 v[108:109], v[40:41], v[108:109], v[48:49]
	v_cvt_pk_bf16_f32 v111, v112, v113
	global_store_dwordx2 v[132:133], v[110:111], off offset:2048
	v_cvt_pk_bf16_f32 v106, v106, v107
	v_cvt_pk_bf16_f32 v107, v108, v109
	global_store_dwordx2 v[132:133], v[106:107], off offset:2560
	v_pk_fma_f32 v[88:89], v[52:53], v[88:89], v[60:61]
	v_cvt_pk_bf16_f32 v86, v86, v87
	v_pk_fma_f32 v[68:69], v[56:57], v[68:69], v[64:65]
	v_cvt_pk_bf16_f32 v87, v88, v89
	global_store_dwordx2 v[132:133], v[86:87], off offset:3072
	v_cvt_pk_bf16_f32 v66, v66, v67
	v_cvt_pk_bf16_f32 v67, v68, v69
	global_store_dwordx2 v[132:133], v[66:67], off offset:3584
	s_add_u32 s8, s8, s80
	s_waitcnt vmcnt(8)
	v_mov_b64_e32 v[66:67], v[90:91]
	v_mov_b64_e32 v[86:87], v[94:95]
	v_mov_b64_e32 v[108:109], v[100:101]
	v_mov_b64_e32 v[112:113], v[104:105]
	v_mov_b64_e32 v[116:117], v[72:73]
	v_mov_b64_e32 v[120:121], v[76:77]
	v_mov_b64_e32 v[124:125], v[80:81]
	v_mov_b64_e32 v[128:129], v[84:85]
	s_addc_u32 s9, s9, s81
	v_lshl_add_u64 v[132:133], v[132:133], 0, s[84:85]
	s_andn2_b64 vcc, exec, s[10:11]
	v_mov_b64_e32 v[68:69], v[92:93]
	v_mov_b64_e32 v[88:89], v[96:97]
	v_mov_b64_e32 v[106:107], v[98:99]
	v_mov_b64_e32 v[110:111], v[102:103]
	v_mov_b64_e32 v[114:115], v[70:71]
	v_mov_b64_e32 v[118:119], v[74:75]
	v_mov_b64_e32 v[122:123], v[78:79]
	v_mov_b64_e32 v[126:127], v[82:83]
	s_cbranch_vccz .LBB0_1524

.LBB0_1720:
	v_add_f32_e32 v0, v126, v127
	v_add_f32_e32 v134, v128, v129
	v_add_f32_e32 v0, v0, v134
	v_add_f32_e32 v134, v122, v123
	v_add_f32_e32 v135, v124, v125
	v_add_f32_e32 v0, 0, v0
	v_add_f32_e32 v134, v134, v135
	v_add_f32_e32 v0, v134, v0
	v_add_f32_e32 v134, v118, v119
	v_add_f32_e32 v135, v120, v121
	v_add_f32_e32 v134, v134, v135
	v_add_f32_e32 v0, v134, v0
	v_add_f32_e32 v134, v114, v115
	v_add_f32_e32 v135, v116, v117
	v_add_f32_e32 v134, v134, v135
	v_add_f32_e32 v0, v134, v0
	v_add_f32_e32 v134, v110, v111
	v_add_f32_e32 v135, v112, v113
	v_add_f32_e32 v134, v134, v135
	v_add_f32_e32 v0, v134, v0
	v_add_f32_e32 v134, v106, v107
	v_add_f32_e32 v135, v108, v109
	v_add_f32_e32 v134, v134, v135
	v_add_f32_e32 v0, v134, v0
	v_add_f32_e32 v134, v86, v87
	v_add_f32_e32 v135, v88, v89
	v_add_f32_e32 v134, v134, v135
	v_add_f32_e32 v0, v134, v0
	v_add_f32_e32 v134, v66, v67
	v_add_f32_e32 v135, v68, v69
	v_add_f32_e32 v134, v134, v135
	v_add_f32_e32 v0, v134, v0
	v_mbcnt_lo_u32_b32 v134, -1, 0
	v_mbcnt_hi_u32_b32 v134, -1, v134
	s_mov_b32 s0, 0xf800000
	v_lshlrev_b32_e32 v134, 2, v134
	v_xor_b32_e32 v134, 4, v134
	ds_bpermute_b32 v134, v134, v0
	s_waitcnt lgkmcnt(0)
	v_add_f32_e32 v0, v0, v134
	v_mbcnt_lo_u32_b32 v134, -1, 0
	v_mbcnt_hi_u32_b32 v134, -1, v134
	s_nop 0
	v_lshlrev_b32_e32 v134, 2, v134
	v_xor_b32_e32 v134, 8, v134
	ds_bpermute_b32 v134, v134, v0
	s_waitcnt lgkmcnt(0)
	v_add_f32_e32 v0, v0, v134
	v_mbcnt_lo_u32_b32 v134, -1, 0
	v_mbcnt_hi_u32_b32 v134, -1, v134
	s_nop 0
	v_lshlrev_b32_e32 v134, 2, v134
	v_xor_b32_e32 v134, 16, v134
	ds_bpermute_b32 v134, v134, v0
	s_waitcnt lgkmcnt(0)
	v_add_f32_e32 v0, v0, v134
	v_mbcnt_lo_u32_b32 v134, -1, 0
	v_mbcnt_hi_u32_b32 v134, -1, v134
	s_nop 0
	v_lshlrev_b32_e32 v134, 2, v134
	v_xor_b32_e32 v134, 32, v134
	ds_bpermute_b32 v134, v134, v0
	s_waitcnt lgkmcnt(0)
	v_add_f32_e32 v0, v0, v134
	v_mbcnt_lo_u32_b32 v134, -1, 0
	v_mbcnt_hi_u32_b32 v134, -1, v134
	s_nop 0
	v_lshlrev_b32_e32 v134, 2, v134
	v_xor_b32_e32 v134, 64, v134
	ds_bpermute_b32 v134, v134, v0
	s_waitcnt lgkmcnt(0)
	v_add_f32_e32 v0, v0, v134
	v_mbcnt_lo_u32_b32 v134, -1, 0
	v_mbcnt_hi_u32_b32 v134, -1, v134
	s_nop 0
	v_lshlrev_b32_e32 v134, 2, v134
	v_xor_b32_e32 v134, 0x80, v134
	ds_bpermute_b32 v134, v134, v0
	s_waitcnt lgkmcnt(0)
	v_add_f32_e32 v144, v0, v134
	v_fmamk_f32 v127, v144, 0xba000000, v127
	v_fmamk_f32 v123, v144, 0xba000000, v123
	v_fmamk_f32 v129, v144, 0xba000000, v129
	v_fmac_f32_e32 v126, 0xba000000, v144
	v_fmamk_f32 v125, v144, 0xba000000, v125
	v_fmac_f32_e32 v122, 0xba000000, v144
	v_mov_b32_e32 v136, v127
	v_mov_b32_e32 v137, v123
	v_fmamk_f32 v128, v144, 0xba000000, v128
	v_fmamk_f32 v124, v144, 0xba000000, v124
	v_mov_b32_e32 v134, v126
	v_mov_b32_e32 v135, v122
	v_pk_mul_f32 v[136:137], v[136:137], v[136:137]
	v_mov_b32_e32 v138, v129
	v_mov_b32_e32 v139, v125
	v_pk_fma_f32 v[134:135], v[134:135], v[134:135], v[136:137]
	v_mov_b32_e32 v136, v128
	v_mov_b32_e32 v137, v124
	v_pk_mul_f32 v[138:139], v[138:139], v[138:139]
	v_fmamk_f32 v119, v144, 0xba000000, v119
	v_pk_fma_f32 v[136:137], v[136:137], v[136:137], v[138:139]
	v_fmamk_f32 v118, v144, 0xba000000, v118
	v_fmamk_f32 v121, v144, 0xba000000, v121
	v_fmac_f32_e32 v120, 0xba000000, v144
	v_pk_add_f32 v[134:135], v[134:135], v[136:137]
	v_pk_mul_f32 v[136:137], v[120:121], v[120:121]
	v_pk_mul_f32 v[138:139], v[118:119], v[118:119]
	v_fmac_f32_e32 v116, 0xba000000, v144
	v_pk_mov_b32 v[140:141], v[138:139], v[136:137] op_sel:[1,0]
	v_mov_b32_e32 v139, v137
	v_pk_add_f32 v[136:137], v[140:141], v[138:139]
	v_fmamk_f32 v138, v144, 0xba000000, v114
	v_fmamk_f32 v139, v144, 0xba000000, v115
	v_mul_f32_e32 v0, v138, v138
	v_fmamk_f32 v117, v144, 0xba000000, v117
	v_pk_fma_f32 v[114:115], v[138:139], v[138:139], v[0:1] op_sel_hi:[1,1,0]
	v_mul_f32_e32 v0, v116, v116
	v_pk_add_f32 v[134:135], v[134:135], v[134:135] op_sel_hi:[0,1]
	v_pk_add_f32 v[136:137], v[136:137], v[136:137] op_sel_hi:[0,1]
	v_pk_fma_f32 v[140:141], v[116:117], v[116:117], v[0:1] op_sel_hi:[1,1,0]
	v_fmamk_f32 v143, v144, 0xba000000, v113
	v_fmamk_f32 v142, v144, 0xba000000, v112
	v_fmamk_f32 v111, v144, 0xba000000, v111
	v_fmac_f32_e32 v110, 0xba000000, v144
	v_mul_f32_e32 v114, v110, v110
	v_mul_f32_e32 v140, v111, v111
	v_mul_f32_e32 v136, v142, v142
	v_mul_f32_e32 v134, v143, v143
	v_pk_add_f32 v[112:113], v[114:115], v[140:141]
	v_pk_add_f32 v[114:115], v[136:137], v[134:135]
	v_fmamk_f32 v107, v144, 0xba000000, v107
	v_fmamk_f32 v106, v144, 0xba000000, v106
	v_fmamk_f32 v109, v144, 0xba000000, v109
	v_fmac_f32_e32 v108, 0xba000000, v144
	v_pk_add_f32 v[112:113], v[112:113], v[114:115]
	v_pk_mul_f32 v[114:115], v[108:109], v[108:109]
	v_pk_mul_f32 v[134:135], v[106:107], v[106:107]
	v_fmamk_f32 v86, v144, 0xba000000, v86
	v_pk_mov_b32 v[136:137], v[134:135], v[114:115] op_sel:[1,0]
	v_mov_b32_e32 v135, v115
	v_fmamk_f32 v87, v144, 0xba000000, v87
	v_fmac_f32_e32 v88, 0xba000000, v144
	v_mul_f32_e32 v0, v86, v86
	v_pk_add_f32 v[114:115], v[136:137], v[134:135]
	v_fmamk_f32 v89, v144, 0xba000000, v89
	v_pk_fma_f32 v[134:135], v[86:87], v[86:87], v[0:1] op_sel_hi:[1,1,0]
	v_mul_f32_e32 v0, v88, v88
	v_pk_add_f32 v[112:113], v[112:113], v[112:113] op_sel_hi:[0,1]
	v_pk_add_f32 v[114:115], v[114:115], v[114:115] op_sel_hi:[0,1]
	v_pk_fma_f32 v[136:137], v[88:89], v[88:89], v[0:1] op_sel_hi:[1,1,0]
	v_fmamk_f32 v69, v144, 0xba000000, v69
	v_fmamk_f32 v68, v144, 0xba000000, v68
	v_fmamk_f32 v67, v144, 0xba000000, v67
	v_fmac_f32_e32 v66, 0xba000000, v144
	v_mul_f32_e32 v134, v66, v66
	v_mul_f32_e32 v136, v67, v67
	v_mul_f32_e32 v114, v68, v68
	v_mul_f32_e32 v112, v69, v69
	v_pk_add_f32 v[134:135], v[134:135], v[136:137]
	v_pk_add_f32 v[112:113], v[114:115], v[112:113]
	s_nop 0
	v_pk_add_f32 v[112:113], v[134:135], v[112:113]
	s_nop 0
	v_add_f32_e32 v0, v112, v113
	v_mbcnt_lo_u32_b32 v112, -1, 0
	v_mbcnt_hi_u32_b32 v112, -1, v112
	s_nop 0
	v_lshlrev_b32_e32 v112, 2, v112
	v_xor_b32_e32 v112, 4, v112
	ds_bpermute_b32 v112, v112, v0
	s_waitcnt lgkmcnt(0)
	v_add_f32_e32 v0, v0, v112
	v_mbcnt_lo_u32_b32 v112, -1, 0
	v_mbcnt_hi_u32_b32 v112, -1, v112
	s_nop 0
	v_lshlrev_b32_e32 v112, 2, v112
	v_xor_b32_e32 v112, 8, v112
	ds_bpermute_b32 v112, v112, v0
	s_waitcnt lgkmcnt(0)
	v_add_f32_e32 v0, v0, v112
	v_mbcnt_lo_u32_b32 v112, -1, 0
	v_mbcnt_hi_u32_b32 v112, -1, v112
	s_nop 0
	v_lshlrev_b32_e32 v112, 2, v112
	v_xor_b32_e32 v112, 16, v112
	ds_bpermute_b32 v112, v112, v0
	s_waitcnt lgkmcnt(0)
	v_add_f32_e32 v0, v0, v112
	v_mbcnt_lo_u32_b32 v112, -1, 0
	v_mbcnt_hi_u32_b32 v112, -1, v112
	s_nop 0
	v_lshlrev_b32_e32 v112, 2, v112
	v_xor_b32_e32 v112, 32, v112
	ds_bpermute_b32 v112, v112, v0
	s_waitcnt lgkmcnt(0)
	v_add_f32_e32 v0, v0, v112
	v_mbcnt_lo_u32_b32 v112, -1, 0
	v_mbcnt_hi_u32_b32 v112, -1, v112
	s_nop 0
	v_lshlrev_b32_e32 v112, 2, v112
	v_xor_b32_e32 v112, 64, v112
	ds_bpermute_b32 v112, v112, v0
	s_waitcnt lgkmcnt(0)
	v_add_f32_e32 v0, v0, v112
	v_mbcnt_lo_u32_b32 v112, -1, 0
	v_mbcnt_hi_u32_b32 v112, -1, v112
	s_nop 0
	v_lshlrev_b32_e32 v112, 2, v112
	v_xor_b32_e32 v112, 0x80, v112
	ds_bpermute_b32 v112, v112, v0
	s_waitcnt lgkmcnt(0)
	v_add_f32_e32 v0, v0, v112
	v_fmamk_f32 v0, v0, 0x3a000000, v190
	v_mul_f32_e32 v112, 0x4f800000, v0
	v_cmp_gt_f32_e32 vcc, s0, v0
	s_nop 1
	v_cndmask_b32_e32 v0, v0, v112, vcc
	v_sqrt_f32_e32 v112, v0
	s_nop 0
	v_add_u32_e32 v113, -1, v112
	v_fma_f32 v114, -v113, v112, v0
	v_cmp_ge_f32_e64 s[4:5], 0, v114
	v_add_u32_e32 v114, 1, v112
	s_nop 0
	v_cndmask_b32_e64 v113, v112, v113, s[4:5]
	v_fma_f32 v112, -v114, v112, v0
	v_cmp_lt_f32_e64 s[4:5], 0, v112
	s_nop 1
	v_cndmask_b32_e64 v112, v113, v114, s[4:5]
	v_mul_f32_e32 v113, 0x37800000, v112
	v_cndmask_b32_e32 v112, v112, v113, vcc
	v_cmp_class_f32_e32 vcc, v0, v191
	s_nop 1
	v_cndmask_b32_e32 v0, v112, v0, vcc
	v_div_scale_f32 v112, s[0:1], v0, v0, 1.0
	v_rcp_f32_e32 v113, v112
	s_movk_i32 s0, 0xf000
	v_fma_f32 v114, -v112, v113, 1.0
	v_fmac_f32_e32 v113, v114, v113
	v_div_scale_f32 v114, vcc, 1.0, v0, 1.0
	v_mul_f32_e32 v115, v114, v113
	v_fma_f32 v134, -v112, v115, v114
	v_fmac_f32_e32 v115, v134, v113
	v_fma_f32 v112, -v112, v115, v114
	v_div_fmas_f32 v112, v112, v113, v115
	v_div_fixup_f32 v0, v112, v0, 1.0
	v_pk_mul_f32 v[112:113], v[126:127], v[0:1] op_sel_hi:[1,0]
	v_pk_mul_f32 v[114:115], v[128:129], v[0:1] op_sel_hi:[1,0]
	v_add_co_u32_e32 v126, vcc, s0, v132
	v_pk_fma_f32 v[114:115], v[20:21], v[114:115], v[28:29]
	v_pk_fma_f32 v[112:113], v[18:19], v[112:113], v[26:27]
	v_addc_co_u32_e32 v127, vcc, -1, v133, vcc
	s_movk_i32 s0, 0xf400
	global_store_dwordx4 v[126:127], v[112:115], off
	v_pk_mul_f32 v[110:111], v[110:111], v[0:1] op_sel_hi:[1,0]
	v_pk_mul_f32 v[106:107], v[106:107], v[0:1] op_sel_hi:[1,0]
	v_pk_mul_f32 v[112:113], v[122:123], v[0:1] op_sel_hi:[1,0]
	v_pk_mul_f32 v[114:115], v[124:125], v[0:1] op_sel_hi:[1,0]
	v_add_co_u32_e32 v122, vcc, s0, v132
	v_pk_fma_f32 v[114:115], v[4:5], v[114:115], v[12:13]
	v_pk_fma_f32 v[112:113], v[2:3], v[112:113], v[10:11]
	v_addc_co_u32_e32 v123, vcc, -1, v133, vcc
	s_movk_i32 s0, 0xf800
	global_store_dwordx4 v[122:123], v[112:115], off
	v_pk_mul_f32 v[108:109], v[108:109], v[0:1] op_sel_hi:[1,0]
	v_pk_mul_f32 v[86:87], v[86:87], v[0:1] op_sel_hi:[1,0]
	v_pk_mul_f32 v[112:113], v[118:119], v[0:1] op_sel_hi:[1,0]
	v_pk_mul_f32 v[114:115], v[120:121], v[0:1] op_sel_hi:[1,0]
	v_add_co_u32_e32 v118, vcc, s0, v132
	v_pk_fma_f32 v[114:115], v[8:9], v[114:115], v[16:17]
	v_pk_fma_f32 v[112:113], v[6:7], v[112:113], v[14:15]
	v_addc_co_u32_e32 v119, vcc, -1, v133, vcc
	s_movk_i32 s0, 0xfc00
	global_store_dwordx4 v[118:119], v[112:115], off
	v_pk_mul_f32 v[88:89], v[88:89], v[0:1] op_sel_hi:[1,0]
	v_pk_mul_f32 v[66:67], v[66:67], v[0:1] op_sel_hi:[1,0]
	v_pk_mul_f32 v[112:113], v[138:139], v[0:1] op_sel_hi:[1,0]
	v_pk_mul_f32 v[114:115], v[116:117], v[0:1] op_sel_hi:[1,0]
	v_add_co_u32_e32 v116, vcc, s0, v132
	v_pk_fma_f32 v[114:115], v[24:25], v[114:115], v[32:33]
	v_pk_fma_f32 v[112:113], v[22:23], v[112:113], v[30:31]
	v_addc_co_u32_e32 v117, vcc, -1, v133, vcc
	global_store_dwordx4 v[116:117], v[112:115], off
	v_pk_mul_f32 v[68:69], v[68:69], v[0:1] op_sel_hi:[1,0]
	v_pk_fma_f32 v[110:111], v[34:35], v[110:111], v[42:43]
	v_pk_mul_f32 v[112:113], v[142:143], v[0:1] op_sel_hi:[1,0]
	v_pk_fma_f32 v[108:109], v[40:41], v[108:109], v[48:49]
	v_pk_fma_f32 v[112:113], v[36:37], v[112:113], v[44:45]
	v_pk_fma_f32 v[106:107], v[38:39], v[106:107], v[46:47]
	v_pk_fma_f32 v[88:89], v[52:53], v[88:89], v[60:61]
	v_pk_fma_f32 v[86:87], v[50:51], v[86:87], v[58:59]
	v_pk_fma_f32 v[68:69], v[56:57], v[68:69], v[64:65]
	v_pk_fma_f32 v[66:67], v[54:55], v[66:67], v[62:63]
	global_store_dwordx4 v[132:133], v[110:113], off
	global_store_dwordx4 v[132:133], v[106:109], off offset:1024
	global_store_dwordx4 v[132:133], v[86:89], off offset:2048
	global_store_dwordx4 v[132:133], v[66:69], off offset:3072
	s_waitcnt vmcnt(8)
	v_mov_b64_e32 v[108:109], v[100:101]
	v_mov_b64_e32 v[86:87], v[94:95]
	v_mov_b64_e32 v[66:67], v[90:91]
	v_mov_b64_e32 v[112:113], v[104:105]
	v_mov_b64_e32 v[116:117], v[72:73]
	v_mov_b64_e32 v[120:121], v[76:77]
	v_mov_b64_e32 v[124:125], v[80:81]
	v_mov_b64_e32 v[128:129], v[84:85]
	v_lshl_add_u64 v[132:133], v[132:133], 0, s[78:79]
	s_and_b64 vcc, exec, s[6:7]
	v_mov_b64_e32 v[68:69], v[92:93]
	v_mov_b64_e32 v[88:89], v[96:97]
	v_mov_b64_e32 v[106:107], v[98:99]
	v_mov_b64_e32 v[110:111], v[102:103]
	v_mov_b64_e32 v[114:115], v[70:71]
	v_mov_b64_e32 v[118:119], v[74:75]
	v_mov_b64_e32 v[122:123], v[78:79]
	v_mov_b64_e32 v[126:127], v[82:83]
	s_cbranch_vccnz .LBB0_1723
